# v20 + skip two redundant grid barriers in the last layer (after w_o phase and after final mlp2 phase)
# baseline (speedup 1.0000x reference)
; #define TM_BEGIN(k) do { if ((TIMEMASK >> (k)) & 1u) tm_t0 = __builtin_amdgcn_s_memrealtime(); } while (0)
; #define TM_END(k) do { if ((TIMEMASK >> (k)) & 1u) tm_acc += __builtin_amdgcn_s_memrealtime() - tm_t0; } while (0)
; #define REP(k) _Pragma("unroll 1") for (int _r = 0; _r < (((DUPMASK >> (k)) & 1u) ? 2 : 1); ++_r)
; #define SEAM(k) do { if (IN(k) && IN((k) + 1)) GRID_BAR(); } while (0)
; #define LAUNDER() do { int _t = F.tid; asm volatile("" : "+v"(_t)); F.tid = _t; F.lane = _t & 63; F.wave = __builtin_amdgcn_readfirstlane(_t >> 6); \
;         asm volatile("" : "+s"(ap)); GAS unsigned char* _w = (GAS unsigned char*)ap->ws; asm volatile("" : "+s"(_w)); F.ws = _w; ws = _w; } while (0)
; __device__ __forceinline__ void xcd_barrier(const XcdBarrier& b) {
;     asm volatile("s_waitcnt vmcnt(0)" ::: "memory");
;     __syncthreads();
;     if (threadIdx.x == 0) {
;         unsigned* bar = b.bar;
;         __builtin_amdgcn_s_waitcnt(0);
;         unsigned nloc = b.st[0], nx = b.st[1];
;         if (nloc == 0u) { xcd_barrier_complete(bar, b.x, nloc, nx); b.st[0] = nloc; b.st[1] = nx; }
; __global__ void __launch_bounds__(512, 2) mk_fwd(Args args_unused) {
;     ...
;         SEAM(p0 + 5); TM_END(6);
;         TM_BEGIN(7);
;         if (IN(p0 + 6)) REP(7) { LAUNDER(); ln_phase(F, ap, l, 0); }
.LBB0_1362:
	v_readlane_b32 s4, v255, 44
	s_add_i32 s4, s4, 9
	s_cmp_lt_i32 s4, s97
	s_cselect_b64 s[6:7], -1, 0
	s_and_b64 s[8:9], s[26:27], s[6:7]
	s_andn2_b64 vcc, exec, s[8:9]
	v_readlane_b32 s100, v255, 42
	s_nop 3
	s_cmp_eq_u32 s100, 3
	s_cbranch_scc1 .LBB0_1416
	s_cbranch_vccnz .LBB0_1416
	s_waitcnt vmcnt(0)
	s_waitcnt vmcnt(0)
	s_barrier
	s_and_saveexec_b64 s[8:9], s[88:89]
	s_cbranch_execz .LBB0_1415
	v_readlane_b32 s5, v255, 28
	s_waitcnt vmcnt(0) expcnt(0) lgkmcnt(0)
	s_nop 0
	v_mov_b32_e32 v1, s5
	ds_read_b32 v3, v1
	v_readlane_b32 s5, v255, 29
	s_waitcnt lgkmcnt(0)
	v_cmp_ne_u32_e32 vcc, 0, v3
	v_mov_b32_e32 v1, s5
	ds_read_b32 v2, v1
	s_cbranch_vccnz .LBB0_1379
	v_readlane_b32 s12, v253, 0
	v_readlane_b32 s13, v253, 1
	s_load_dwordx2 s[10:11], s[12:13], 0x4
	s_mov_b32 s22, 1
	s_waitcnt lgkmcnt(0)
	s_mul_i32 s5, s10, s3
	s_mul_i32 s5, s5, s11
	s_branch .LBB0_1367

; #define TM_END(k) do { if ((TIMEMASK >> (k)) & 1u) tm_acc += __builtin_amdgcn_s_memrealtime() - tm_t0; } while (0)
; #define SEAM(k) do { if (IN(k) && IN((k) + 1)) GRID_BAR(); } while (0)
; __device__ __forceinline__ void xcd_barrier(const XcdBarrier& b) {
;     asm volatile("s_waitcnt vmcnt(0)" ::: "memory");
;     __syncthreads();
;     if (threadIdx.x == 0) {
;         unsigned* bar = b.bar;
;         __builtin_amdgcn_s_waitcnt(0);
;         unsigned nloc = b.st[0], nx = b.st[1];
;         if (nloc == 0u) { xcd_barrier_complete(bar, b.x, nloc, nx); b.st[0] = nloc; b.st[1] = nx; }
; __global__ void __launch_bounds__(512, 2) mk_fwd(Args args_unused) {
;     ...
;         SEAM(p0 + 8); TM_END(9);
.LBB0_1864:
	v_readlane_b32 s4, v255, 44
	s_add_i32 s4, s4, 12
	s_cmp_lt_i32 s4, s97
	s_cselect_b64 s[6:7], -1, 0
	s_and_b64 s[8:9], s[26:27], s[6:7]
	s_andn2_b64 vcc, exec, s[8:9]
	v_readlane_b32 s100, v255, 42
	s_nop 3
	s_cmp_eq_u32 s100, 3
	s_cbranch_scc1 .LBB0_1918
	s_cbranch_vccnz .LBB0_1918
	s_waitcnt vmcnt(0)
	s_waitcnt vmcnt(0) lgkmcnt(0)
	s_barrier
	s_and_saveexec_b64 s[8:9], s[88:89]
	s_cbranch_execz .LBB0_1917
	v_readlane_b32 s5, v255, 28
	s_waitcnt vmcnt(0) expcnt(0) lgkmcnt(0)
	s_nop 0
	v_mov_b32_e32 v1, s5
	ds_read_b32 v3, v1
	v_readlane_b32 s5, v255, 29
	s_waitcnt lgkmcnt(0)
	v_cmp_ne_u32_e32 vcc, 0, v3
	v_mov_b32_e32 v1, s5
	ds_read_b32 v2, v1
	s_cbranch_vccnz .LBB0_1881
	v_readlane_b32 s12, v253, 0
	v_readlane_b32 s13, v253, 1
	s_load_dwordx2 s[10:11], s[12:13], 0x4
	s_mov_b32 s22, 1
	s_waitcnt lgkmcnt(0)
	s_mul_i32 s5, s10, s3
	s_mul_i32 s5, s5, s11
	s_branch .LBB0_1869
